# XCD barrier first-use poll: 16 counter loads in flight instead of serialized
# baseline (speedup 1.0000x reference)
.LBB0_1462:
	v_readlane_b32 s2, v252, 16
	v_readlane_b32 s3, v252, 17
	s_mov_b64 s[4:5], -1
	s_nop 3
	global_load_dword v0, v1, s[2:3] sc1
	v_readlane_b32 s2, v252, 18
	v_readlane_b32 s3, v252, 19
	s_nop 4
	global_load_dword v2, v1, s[2:3] sc1
	v_readlane_b32 s2, v252, 20
	v_readlane_b32 s3, v252, 21
	s_nop 1
	s_nop 2
	global_load_dword v3, v1, s[2:3] sc1
	v_readlane_b32 s2, v252, 22
	v_readlane_b32 s3, v252, 23
	s_nop 1
	s_nop 2
	global_load_dword v4, v1, s[2:3] sc1
	v_readlane_b32 s2, v252, 24
	v_readlane_b32 s3, v252, 25
	s_nop 1
	s_nop 2
	global_load_dword v5, v1, s[2:3] sc1
	v_readlane_b32 s2, v252, 26
	v_readlane_b32 s3, v252, 27
	s_nop 1
	s_nop 2
	global_load_dword v6, v1, s[2:3] sc1
	v_readlane_b32 s2, v252, 28
	v_readlane_b32 s3, v252, 29
	s_nop 1
	s_nop 2
	global_load_dword v7, v1, s[2:3] sc1
	v_readlane_b32 s2, v252, 30
	v_readlane_b32 s3, v252, 31
	s_nop 1
	s_nop 2
	global_load_dword v8, v1, s[2:3] sc1
	v_readlane_b32 s2, v252, 32
	v_readlane_b32 s3, v252, 33
	s_nop 1
	s_nop 2
	global_load_dword v9, v1, s[2:3] sc1
	v_readlane_b32 s2, v252, 34
	v_readlane_b32 s3, v252, 35
	s_nop 1
	s_nop 2
	global_load_dword v10, v1, s[2:3] sc1
	v_readlane_b32 s2, v252, 36
	v_readlane_b32 s3, v252, 37
	s_nop 1
	s_nop 2
	global_load_dword v11, v1, s[2:3] sc1
	v_readlane_b32 s2, v252, 38
	v_readlane_b32 s3, v252, 39
	s_nop 1
	s_nop 2
	global_load_dword v12, v1, s[2:3] sc1
	v_readlane_b32 s2, v252, 40
	v_readlane_b32 s3, v252, 41
	s_nop 1
	s_nop 2
	global_load_dword v13, v1, s[2:3] sc1
	v_readlane_b32 s2, v252, 42
	v_readlane_b32 s3, v252, 43
	s_nop 1
	s_nop 2
	global_load_dword v14, v1, s[2:3] sc1
	v_readlane_b32 s2, v252, 44
	v_readlane_b32 s3, v252, 45
	s_nop 1
	s_nop 2
	global_load_dword v15, v1, s[2:3] sc1
	v_readlane_b32 s2, v252, 46
	v_readlane_b32 s3, v252, 47
	s_nop 1
	s_nop 2
	global_load_dword v16, v1, s[2:3] sc1
	s_mov_b64 s[2:3], -1
	s_waitcnt vmcnt(0)
	v_add_u32_e32 v17, v2, v0
	v_add_u32_e32 v17, v17, v3
	v_add_u32_e32 v17, v17, v4
	v_add_u32_e32 v17, v17, v5
	v_add_u32_e32 v17, v17, v6
	v_add_u32_e32 v17, v17, v7
	v_add_u32_e32 v17, v17, v8
	v_add_u32_e32 v17, v17, v9
	v_add_u32_e32 v17, v17, v10
	v_add_u32_e32 v17, v17, v11
	v_add_u32_e32 v17, v17, v12
	v_add_u32_e32 v17, v17, v13
	v_add_u32_e32 v17, v17, v14
	v_add_u32_e32 v17, v17, v15
	v_add_u32_e32 v17, v17, v16
	v_cmp_eq_u32_e32 vcc, s8, v17
	s_cbranch_vccnz .LBB0_1461
	s_and_b32 s2, s9, 0xff
	s_cmp_eq_u32 s2, 0
	s_mov_b64 s[2:3], -1
	s_mov_b64 s[6:7], -1
	s_sleep 1
	s_cbranch_scc1 .LBB0_1466
	s_and_b64 vcc, exec, s[6:7]
	s_cbranch_vccz .LBB0_1461
